# GLA value-tile transposes: lane pairs exchanged with DPP so each lane writes one 32-bit LDS word instead of two 16-bit ones (pass1 and pass3)
# baseline (speedup 1.0000x reference)
.LBB0_615:
	s_cmp_gt_i32 s20, 3
	s_cselect_b32 s0, 0x87, 3
	s_sub_i32 s3, s0, s20
	s_and_b64 s[0:1], s[42:43], exec
	s_cselect_b32 s0, s20, s3
	s_lshl_b32 s1, s21, 1
	s_sub_i32 s3, s19, s22
	s_add_i32 s1, s3, s1
	v_lshlrev_b32_e32 v0, 4, v16
	s_add_i32 s1, s1, 8
	v_and_b32_e32 v23, 0x70, v0
	s_mul_hi_u32 s3, s1, 0x84
	s_mulk_i32 s1, 0x84
	s_ashr_i32 s19, s0, 31
	v_mov_b32_e32 v0, v207
	s_add_u32 s0, s1, s0
	s_addc_u32 s1, s3, s19
	v_and_b32_e32 v6, 63, v0
	v_or_b32_e32 v1, s9, v6
	s_movk_i32 s3, 0x1200
	v_mul_lo_u32 v128, v1, s3
	v_ashrrev_i32_e32 v0, 2, v0
	v_lshl_add_u64 v[2:3], v[128:129], 1, s[36:37]
	s_lshl_b32 s26, s2, 1
	v_and_b32_e32 v0, -16, v0
	v_lshl_add_u64 v[2:3], v[2:3], 0, s[26:27]
	s_lshl_b32 s26, s18, 1
	v_lshl_add_u64 v[2:3], v[2:3], 0, s[26:27]
	v_ashrrev_i32_e32 v1, 31, v0
	v_lshl_add_u64 v[4:5], v[0:1], 1, v[2:3]
	s_movk_i32 s2, 0x90
	v_lshlrev_b32_e32 v9, 1, v6
	v_mul_lo_u32 v10, v0, s2
	v_readlane_b32 s2, v252, 12
	v_ashrrev_i32_e32 v8, 3, v16
	v_lshlrev_b32_e32 v44, 1, v8
	v_add3_u32 v11, s2, v9, v10
	v_add3_u32 v9, s2, v10, v9
	s_and_b64 s[2:3], s[42:43], exec
	s_cselect_b32 s2, 0x7e00, 0
	s_add_i32 s9, s2, 0
	v_readlane_b32 s2, v251, 5
	s_waitcnt vmcnt(0) lgkmcnt(0)
	v_and_b32_e32 v164, 1, v207
	v_sub_u32_e32 v164, 0, v164
	v_and_b32_e32 v165, 0x6060606, v164
	v_xor_b32_e32 v165, 0x5040100, v165
	v_and_b32_e32 v166, 0x8e, v164
	v_add_u32_e32 v166, v166, v11
	v_mov_b32_dpp v167, v154 quad_perm:[1,0,3,2] row_mask:0xf bank_mask:0xf
	v_perm_b32 v167, v167, v154, v165
	ds_write_b32 v166, v167
	v_mov_b32_dpp v168, v155 quad_perm:[1,0,3,2] row_mask:0xf bank_mask:0xf
	v_perm_b32 v168, v168, v155, v165
	ds_write_b32 v166, v168 offset:288
	v_mov_b32_dpp v167, v156 quad_perm:[1,0,3,2] row_mask:0xf bank_mask:0xf
	v_perm_b32 v167, v167, v156, v165
	ds_write_b32 v166, v167 offset:576
	v_mov_b32_dpp v168, v157 quad_perm:[1,0,3,2] row_mask:0xf bank_mask:0xf
	v_perm_b32 v168, v168, v157, v165
	ds_write_b32 v166, v168 offset:864
	v_mov_b32_dpp v167, v158 quad_perm:[1,0,3,2] row_mask:0xf bank_mask:0xf
	v_perm_b32 v167, v167, v158, v165
	ds_write_b32 v166, v167 offset:1152
	v_mov_b32_dpp v168, v159 quad_perm:[1,0,3,2] row_mask:0xf bank_mask:0xf
	v_perm_b32 v168, v168, v159, v165
	ds_write_b32 v166, v168 offset:1440
	v_mov_b32_dpp v167, v160 quad_perm:[1,0,3,2] row_mask:0xf bank_mask:0xf
	v_perm_b32 v167, v167, v160, v165
	ds_write_b32 v166, v167 offset:1728
	v_mov_b32_dpp v168, v161 quad_perm:[1,0,3,2] row_mask:0xf bank_mask:0xf
	v_perm_b32 v168, v168, v161, v165
	ds_write_b32 v166, v168 offset:2016
	v_lshlrev_b32_e32 v0, 2, v23
	v_add_u32_e32 v22, s9, v0
	v_lshlrev_b32_e32 v1, 9, v8
	v_add3_u32 v25, 0, v1, v0
	ds_read_b128 v[36:39], v22
	ds_read_b128 v[8:11], v22 offset:16
	ds_read_b128 v[0:3], v22 offset:32
	ds_read_b128 v[40:43], v25
	ds_read_b128 v[12:15], v25 offset:16
	ds_read_b128 v[4:7], v25 offset:32
	v_mul_u32_u24_e32 v23, 0x90, v23
	v_add3_u32 v23, s2, v44, v23
	s_waitcnt lgkmcnt(2)
	v_sub_f32_e32 v36, v36, v40
	s_waitcnt lgkmcnt(1)
	v_sub_f32_e32 v8, v8, v12
	s_waitcnt lgkmcnt(0)
	v_sub_f32_e32 v0, v0, v4
	v_mul_f32_e32 v36, 0x3fb8aa3b, v36
	v_mul_f32_e32 v8, 0x3fb8aa3b, v8
	v_mul_f32_e32 v0, 0x3fb8aa3b, v0
	v_exp_f32_e32 v36, v36
	v_exp_f32_e32 v8, v8
	v_exp_f32_e32 v0, v0
	s_movk_i32 s2, 0x80
	v_mul_f32_e32 v35, v35, v36
	v_mul_f32_e32 v8, v31, v8
	v_mul_f32_e32 v0, v27, v0
	v_cvt_pk_bf16_f32 v35, v35, s0
	v_cvt_pk_bf16_f32 v8, v8, s0
	v_cvt_pk_bf16_f32 v0, v0, s0
	ds_write_b16 v23, v35
	v_sub_f32_e32 v35, v37, v41
	ds_write_b16 v23, v8 offset:576
	v_sub_f32_e32 v8, v9, v13
	ds_write_b16 v23, v0 offset:1152
	v_sub_f32_e32 v0, v1, v5
	v_mul_f32_e32 v35, 0x3fb8aa3b, v35
	v_mul_f32_e32 v8, 0x3fb8aa3b, v8
	v_mul_f32_e32 v0, 0x3fb8aa3b, v0
	v_exp_f32_e32 v35, v35
	v_exp_f32_e32 v8, v8
	v_exp_f32_e32 v0, v0
	v_cmp_gt_i32_e32 vcc, s2, v16
	v_mul_f32_e32 v34, v34, v35
	v_mul_f32_e32 v8, v30, v8
	v_mul_f32_e32 v0, v26, v0
	v_cvt_pk_bf16_f32 v34, v34, s0
	v_cvt_pk_bf16_f32 v8, v8, s0
	v_cvt_pk_bf16_f32 v0, v0, s0
	ds_write_b16 v23, v34 offset:144
	v_sub_f32_e32 v34, v38, v42
	ds_write_b16 v23, v8 offset:720
	v_sub_f32_e32 v8, v10, v14
	ds_write_b16 v23, v0 offset:1296
	v_sub_f32_e32 v0, v2, v6
	v_mul_f32_e32 v34, 0x3fb8aa3b, v34
	v_mul_f32_e32 v8, 0x3fb8aa3b, v8
	v_mul_f32_e32 v0, 0x3fb8aa3b, v0
	v_exp_f32_e32 v34, v34
	v_exp_f32_e32 v8, v8
	v_exp_f32_e32 v0, v0
	v_mul_f32_e32 v33, v33, v34
	v_mul_f32_e32 v8, v29, v8
	v_mul_f32_e32 v0, v24, v0
	v_cvt_pk_bf16_f32 v33, v33, s0
	v_cvt_pk_bf16_f32 v8, v8, s0
	v_cvt_pk_bf16_f32 v0, v0, s0
	ds_write_b16 v23, v33 offset:288
	v_sub_f32_e32 v33, v39, v43
	ds_write_b16 v23, v8 offset:864
	v_sub_f32_e32 v8, v11, v15
	ds_write_b16 v23, v0 offset:1440
	v_sub_f32_e32 v0, v3, v7
	v_mul_f32_e32 v33, 0x3fb8aa3b, v33
	v_mul_f32_e32 v8, 0x3fb8aa3b, v8
	v_mul_f32_e32 v0, 0x3fb8aa3b, v0
	v_exp_f32_e32 v33, v33
	v_exp_f32_e32 v8, v8
	v_exp_f32_e32 v0, v0
	v_mul_f32_e32 v32, v32, v33
	v_mul_f32_e32 v8, v28, v8
	v_mul_f32_e32 v0, v21, v0
	v_cvt_pk_bf16_f32 v32, v32, s0
	v_cvt_pk_bf16_f32 v8, v8, s0
	v_cvt_pk_bf16_f32 v0, v0, s0
	ds_write_b16 v23, v32 offset:432
	ds_write_b16 v23, v8 offset:1008
	ds_write_b16 v23, v0 offset:1584
	ds_read_b128 v[0:3], v22 offset:48
	ds_read_b128 v[4:7], v25 offset:48
	s_waitcnt lgkmcnt(0)
	v_sub_f32_e32 v0, v0, v4
	v_mul_f32_e32 v0, 0x3fb8aa3b, v0
	v_exp_f32_e32 v0, v0
	s_nop 0
	v_mul_f32_e32 v0, v20, v0
	v_cvt_pk_bf16_f32 v0, v0, s0
	ds_write_b16 v23, v0 offset:1728
	v_sub_f32_e32 v0, v1, v5
	v_mul_f32_e32 v0, 0x3fb8aa3b, v0
	v_exp_f32_e32 v0, v0
	s_nop 0
	v_mul_f32_e32 v0, v19, v0
	v_cvt_pk_bf16_f32 v0, v0, s0
	ds_write_b16 v23, v0 offset:1872
	v_sub_f32_e32 v0, v2, v6
	v_mul_f32_e32 v0, 0x3fb8aa3b, v0
	v_exp_f32_e32 v0, v0
	s_nop 0
	v_mul_f32_e32 v0, v18, v0
	v_cvt_pk_bf16_f32 v0, v0, s0
	ds_write_b16 v23, v0 offset:2016
	v_sub_f32_e32 v0, v3, v7
	v_mul_f32_e32 v0, 0x3fb8aa3b, v0
	v_exp_f32_e32 v0, v0
	s_nop 0
	v_mul_f32_e32 v0, v17, v0
	v_cvt_pk_bf16_f32 v0, v0, s0
	ds_write_b16 v23, v0 offset:2160
	s_and_saveexec_b64 s[2:3], vcc
	s_cbranch_execz .LBB0_594
	v_lshl_add_u32 v0, v16, 2, s9
	ds_read_b32 v0, v0
	s_lshl_b64 s[18:19], s[0:1], 9
	s_add_u32 s18, s90, s18
	s_addc_u32 s19, s91, s19
	v_ashrrev_i32_e32 v17, 31, v16
	s_waitcnt lgkmcnt(0)
	v_mul_f32_e32 v0, 0x3fb8aa3b, v0
	v_exp_f32_e32 v2, v0
	v_lshl_add_u64 v[0:1], v[16:17], 2, s[18:19]
	global_store_dword v[0:1], v2, off
	s_branch .LBB0_594
